# k39: k36 + GEMM phases no longer drain the caller's stores before their first DMA loads; no drain between the S5 chunk-state GEMM and the sample S5 item
# speedup vs baseline: 1.0025x; 1.0025x over previous
; #define PG8_STAGE(bufoff, gbase, voff) do { _Pragma("unroll") for (int _i = 0; _i < 2; ++_i) \
;         __builtin_amdgcn_global_load_lds((const unsigned*)((const char*)(gbase) + (voff)[_i]), (LAS unsigned*)(lds + (bufoff) + ldsw + _i * 8192), 16, 0, 0); } while (0)
; #define PG8_WAIT_V(n) asm volatile("s_waitcnt vmcnt(" #n ")" ::: "memory")
; #define PG8_BAR __builtin_amdgcn_s_barrier()
; template <class Epi, class Sched>
; __device__ __forceinline__ void gemm_phase(LAS unsigned char* lds, const Gemm g, const Sched& S, const Epi& E) {
;     ...
;     for (int i = 0; i < 2; ++i) { int R, C; stage_rc(tid * 16 + i * 8192, R, C); const int Rb = Epi::PERM ? ((R & ~31) + perm32(R & 31)) : R;
;         voffA[i] = (unsigned)R * g.lda + (g.aplane ? (unsigned)(C >> 4) * g.aplane + (unsigned)((C & 15) * 2) : (unsigned)(C * 2)); voffB[i] = (unsigned)Rb * g.ldb + (unsigned)(C * 2); }
;     const size_t kstepA = g.kstepA, kstepB = g.kstepB;
;     const size_t hstepA = (size_t)HALF * g.lda, hstepB = (size_t)HALF * g.ldb;
;     const unsigned ldsw = (unsigned)wid * 1024u;
;     const int aoff = lds_byte(wr * 64 + fr, fq * 8), boff = lds_byte(wc * 32 + fr, fq * 8);
;     ...
;     Unit cur, nxt; int ui = 0;
;     if (!S.next(0, cur)) return;
;     f32x4 acc[2][2][4][2];
; #pragma unroll
;     for (int a = 0; a < 2; ++a)
; #pragma unroll
;         for (int b = 0; b < 2; ++b)
; #pragma unroll
;             for (int m = 0; m < 4; ++m)
; #pragma unroll
;                 for (int n = 0; n < 2; ++n) acc[a][b][m][n] = (f32x4){0.f, 0.f, 0.f, 0.f};
;     bf16x8 At[4][2], B0[2][2], B1[2][2];
;     const char* cA = cur.a; const char* cB = cur.b;
;     PG8_WAIT_V(0);
;     PG8_STAGE(PG8_SB(0, 0), cB, voffB); PG8_STAGE(PG8_SB(0, 1), cB + hstepB, voffB); PG8_STAGE(PG8_SA(0, 0), cA, voffA); PG8_STAGE(PG8_SA(0, 1), cA + hstepA, voffA);
;     if (wr == 1) PG8_BAR;
;     PG8_WAIT_V(2); PG8_BAR;
;     PG8_STAGE(PG8_SB(1, 0), cB + kstepB, voffB); PG8_STAGE(PG8_SA(1, 0), cA + kstepA, voffA); PG8_STAGE(PG8_SB(1, 1), cB + hstepB + kstepB, voffB);
.LBB0_266:
.LBB0_267:
	s_add_u32 s3, s92, 0x1d000000
	v_writelane_b32 v255, s3, 26
	s_addc_u32 s3, s93, 0
	v_writelane_b32 v255, s3, 27
	s_add_u32 s3, s92, 0x21000000
	v_writelane_b32 v255, s3, 28
	s_addc_u32 s3, s93, 0
	v_writelane_b32 v255, s3, 29
	s_andn2_b64 vcc, exec, s[8:9]
	s_ashr_i32 s3, s94, 31
	s_cbranch_vccnz .LBB0_549
	v_ashrrev_i32_e32 v1, 31, v8
	v_lshrrev_b32_e32 v1, 26, v1
	v_add_u32_e32 v1, v8, v1
	v_ashrrev_i32_e32 v9, 6, v1
	v_bfe_i32 v1, v8, 27, 1
	v_lshlrev_b32_e32 v0, 4, v8
	v_lshrrev_b32_e32 v1, 22, v1
	v_add_u32_e32 v1, v0, v1
	v_and_b32_e32 v1, 0xfffffc00, v1
	v_sub_u32_e32 v1, v0, v1
	v_lshrrev_b32_e32 v2, 4, v1
	v_bitop3_b32 v1, v2, v1, 32 bitop3:0x6c
	v_ashrrev_i32_e32 v3, 31, v1
	v_lshrrev_b32_e32 v3, 26, v3
	v_add_u32_e32 v3, v1, v3
	v_lshlrev_b32_e32 v2, 3, v9
	v_ashrrev_i32_e32 v10, 6, v3
	v_and_b32_e32 v3, 0xc0, v3
	v_and_b32_e32 v2, -16, v2
	v_sub_u32_e32 v1, v1, v3
	v_mov_b32_e32 v3, 1
	v_add_u32_e32 v2, v10, v2
	v_ashrrev_i16_sdwa v1, v3, sext(v1) dst_sel:DWORD dst_unused:UNUSED_PAD src0_sel:DWORD src1_sel:BYTE_0
	v_lshlrev_b32_e32 v4, 5, v9
	v_bfe_i32 v11, v1, 0, 16
	v_lshlrev_b32_e32 v1, 1, v2
	v_lshrrev_b32_e32 v5, 2, v2
	v_and_b32_e32 v6, 3, v10
	s_mov_b32 s8, 0x1fffe0
	v_and_b32_e32 v4, 32, v4
	v_and_b32_e32 v1, 24, v1
	v_and_b32_e32 v5, 4, v5
	v_and_or_b32 v6, v2, s8, v6
	v_or3_b32 v1, v6, v5, v1
	v_add_lshl_u32 v4, v4, v11, 1
	v_add_u32_e32 v0, 0x2000, v0
	v_lshl_add_u32 v146, v1, 11, v4
	v_ashrrev_i32_e32 v1, 31, v0
	v_lshrrev_b32_e32 v1, 22, v1
	v_add_u32_e32 v1, v0, v1
	v_ashrrev_i32_e32 v12, 10, v1
	v_mul_i32_i24_e32 v1, 0x400, v12
	v_sub_u32_e32 v0, v0, v1
	v_lshrrev_b32_e32 v1, 4, v0
	v_bitop3_b32 v0, v1, v0, 32 bitop3:0x6c
	v_lshl_add_u32 v144, v2, 11, v4
	v_ashrrev_i32_e32 v2, 31, v0
	v_lshrrev_b32_e32 v2, 26, v2
	v_add_u32_e32 v2, v0, v2
	v_lshlrev_b32_e32 v1, 3, v12
	v_ashrrev_i32_e32 v13, 6, v2
	v_and_b32_e32 v2, 0xc0, v2
	s_ashr_i32 s7, s11, 6
	v_and_b32_e32 v1, -16, v1
	v_sub_u32_e32 v0, v0, v2
	v_add_u32_e32 v1, v13, v1
	v_ashrrev_i16_sdwa v0, v3, sext(v0) dst_sel:DWORD dst_unused:UNUSED_PAD src0_sel:DWORD src1_sel:BYTE_0
	s_lshl_b32 s44, s7, 10
	v_lshlrev_b32_e32 v4, 5, v12
	v_bfe_i32 v14, v0, 0, 16
	v_lshlrev_b32_e32 v0, 1, v1
	v_lshrrev_b32_e32 v2, 2, v1
	v_and_b32_e32 v3, 3, v13
	s_add_i32 s45, s44, 0
	v_and_b32_e32 v4, 32, v4
	v_and_b32_e32 v0, 24, v0
	v_and_b32_e32 v2, 4, v2
	v_and_or_b32 v3, v1, s8, v3
	s_nop 0
	s_add_i32 m0, s45, 0x10000
	v_or3_b32 v0, v3, v2, v0
	v_add_lshl_u32 v2, v4, v14, 1
	s_ashr_i32 s8, s11, 8
	global_load_lds_dwordx4 v146, s[4:5]
	s_add_i32 m0, s45, 0x12000
	v_lshl_add_u32 v150, v0, 11, v2
	s_add_u32 s12, s4, 0x40000
	global_load_lds_dwordx4 v150, s[4:5]
	s_addc_u32 s13, s5, 0
	s_add_i32 m0, s45, 0x14000
	s_add_i32 s21, s45, 0x2000
	global_load_lds_dwordx4 v146, s[12:13]
	s_add_i32 m0, s45, 0x16000
	v_lshl_add_u32 v148, v1, 11, v2
	global_load_lds_dwordx4 v150, s[12:13]
	s_mov_b32 m0, s45
	s_add_u32 s12, s0, 0x40000
	global_load_lds_dwordx4 v144, s[0:1]
	s_mov_b32 m0, s21
	s_addc_u32 s13, s1, 0
	s_add_i32 s20, s45, 0x4000
	global_load_lds_dwordx4 v148, s[0:1]
	s_mov_b32 m0, s20
	s_add_i32 s50, s45, 0x6000
	global_load_lds_dwordx4 v144, s[12:13]
	s_mov_b32 m0, s50
	v_writelane_b32 v255, s96, 30
	global_load_lds_dwordx4 v148, s[12:13]
	s_cmp_eq_u32 s8, 1
	v_writelane_b32 v255, s97, 31
	v_mov_b32_e32 v153, 0
	s_cselect_b64 s[12:13], -1, 0
	v_mov_b32_e32 v147, v153
	v_mov_b32_e32 v151, v153
	v_mov_b32_e32 v145, v153
	v_mov_b32_e32 v149, v153
	v_writelane_b32 v255, s12, 20
	s_mov_b32 s51, 0
	v_lshl_add_u64 v[4:5], s[4:5], 0, v[146:147]
	v_lshl_add_u64 v[2:3], s[4:5], 0, v[150:151]
	v_lshl_add_u64 v[0:1], s[0:1], 0, v[144:145]
	v_writelane_b32 v255, s13, 21
	s_cmp_lg_u32 s8, 1
	v_lshl_add_u64 v[6:7], s[0:1], 0, v[148:149]
	s_cbranch_scc1 .LBB0_270
	s_barrier

; #define PG8_STAGE(bufoff, gbase, voff) do { _Pragma("unroll") for (int _i = 0; _i < 2; ++_i) \
;         __builtin_amdgcn_global_load_lds((const unsigned*)((const char*)(gbase) + (voff)[_i]), (LAS unsigned*)(lds + (bufoff) + ldsw + _i * 8192), 16, 0, 0); } while (0)
; #define PG8_WAIT_V(n) asm volatile("s_waitcnt vmcnt(" #n ")" ::: "memory")
; #define PG8_BAR __builtin_amdgcn_s_barrier()
; #define SB WSP(float, WS_SB)
; template <class Epi, class Sched>
; __device__ __forceinline__ void gemm_phase(LAS unsigned char* lds, const Gemm g, const Sched& S, const Epi& E) {
;     ...
;     for (int i = 0; i < 2; ++i) { int R, C; stage_rc(tid * 16 + i * 8192, R, C); const int Rb = Epi::PERM ? ((R & ~31) + perm32(R & 31)) : R;
;         voffA[i] = (unsigned)R * g.lda + (g.aplane ? (unsigned)(C >> 4) * g.aplane + (unsigned)((C & 15) * 2) : (unsigned)(C * 2)); voffB[i] = (unsigned)Rb * g.ldb + (unsigned)(C * 2); }
;     const size_t kstepA = g.kstepA, kstepB = g.kstepB;
;     const size_t hstepA = (size_t)HALF * g.lda, hstepB = (size_t)HALF * g.ldb;
;     const unsigned ldsw = (unsigned)wid * 1024u;
;     const int aoff = lds_byte(wr * 64 + fr, fq * 8), boff = lds_byte(wc * 32 + fr, fq * 8);
;     ...
;     Unit cur, nxt; int ui = 0;
;     if (!S.next(0, cur)) return;
;     f32x4 acc[2][2][4][2];
; #pragma unroll
;     for (int a = 0; a < 2; ++a)
; #pragma unroll
;         for (int b = 0; b < 2; ++b)
; #pragma unroll
;             for (int m = 0; m < 4; ++m)
; #pragma unroll
;                 for (int n = 0; n < 2; ++n) acc[a][b][m][n] = (f32x4){0.f, 0.f, 0.f, 0.f};
;     bf16x8 At[4][2], B0[2][2], B1[2][2];
;     const char* cA = cur.a; const char* cB = cur.b;
;     PG8_WAIT_V(0);
;     PG8_STAGE(PG8_SB(0, 0), cB, voffB); PG8_STAGE(PG8_SB(0, 1), cB + hstepB, voffB); PG8_STAGE(PG8_SA(0, 0), cA, voffA); PG8_STAGE(PG8_SA(0, 1), cA + hstepA, voffA);
;     if (wr == 1) PG8_BAR;
;     PG8_WAIT_V(2); PG8_BAR;
;     PG8_STAGE(PG8_SB(1, 0), cB + kstepB, voffB); PG8_STAGE(PG8_SA(1, 0), cA + kstepA, voffA); PG8_STAGE(PG8_SB(1, 1), cB + hstepB + kstepB, voffB);
; __global__ void __launch_bounds__(NTHR, 2) hymba_fwd(Params P) {
;     ...
;     __syncthreads();
;     {
;         pg8::Gemm g{UXR * 32, 256 * 2, 128, 128, 4, 0}; pg8::S5Order S{G, blk, (const char*)UX, (const char*)W1, (size_t)256 * 256 * 2};
;         EpiS E{SB};
;         pg8::gemm_phase<EpiS, pg8::S5Order>(lds, g, S, E);
.LBB0_602:
	s_or_b64 exec, exec, s[0:1]
	s_cmpk_lt_i32 s2, 0x200
	s_cselect_b64 s[6:7], -1, 0
	s_lshr_b32 s0, s33, 28
	s_add_i32 s0, s2, s0
	s_and_b32 s16, s2, 31
	s_and_b32 s0, s0, -16
	s_bfe_u32 s88, s2, 0x30005
	s_lshl_b32 s88, s88, 1
	s_mul_i32 s4, s88, 0x30000
	s_ashr_i32 s17, s16, 31
	s_mul_i32 s1, s16, 0x306000
	s_ashr_i32 s5, s4, 31
	s_mul_hi_i32 s0, s16, 0x306000
	s_add_u32 s1, s22, s1
	s_addc_u32 s0, s23, s0
	s_add_u32 s30, s1, s4
	v_mov_b32_e32 v8, v208
	v_writelane_b32 v255, s6, 20
	s_waitcnt lgkmcnt(0)
	s_barrier
	s_addc_u32 s31, s0, s5
	s_barrier
	v_writelane_b32 v255, s7, 21
	v_readfirstlane_b32 s4, v8
	s_and_b64 vcc, exec, s[6:7]
	s_cbranch_vccz .LBB0_616
	v_lshlrev_b32_e32 v1, 4, v8
	v_add_u32_e32 v0, 0x2000, v1
	v_ashrrev_i32_e32 v2, 31, v0
	v_lshrrev_b32_e32 v2, 22, v2
	v_add_u32_e32 v2, v0, v2
	v_ashrrev_i32_e32 v2, 10, v2
	v_mul_i32_i24_e32 v3, 0x400, v2
	v_sub_u32_e32 v0, v0, v3
	v_lshrrev_b32_e32 v3, 4, v0
	v_bitop3_b32 v0, v3, v0, 32 bitop3:0x6c
	v_ashrrev_i32_e32 v3, 31, v0
	v_lshrrev_b32_e32 v3, 26, v3
	v_add_u32_e32 v3, v0, v3
	v_lshlrev_b32_e32 v5, 3, v2
	v_ashrrev_i32_e32 v4, 6, v3
	v_and_b32_e32 v5, -16, v5
	v_and_b32_e32 v3, 0xc0, v3
	s_lshl_b64 s[0:1], s[16:17], 17
	v_readlane_b32 s5, v255, 14
	v_add_u32_e32 v5, v4, v5
	v_sub_u32_e32 v0, v0, v3
	v_mov_b32_e32 v3, 1
	s_add_u32 s70, s5, s0
	v_and_b32_e32 v4, 3, v4
	s_mov_b32 s5, 0x7fffe0
	v_lshrrev_b32_e32 v6, 2, v5
	v_lshlrev_b32_e32 v7, 1, v5
	v_lshlrev_b32_e32 v2, 5, v2
	v_ashrrev_i16_sdwa v0, v3, sext(v0) dst_sel:DWORD dst_unused:UNUSED_PAD src0_sel:DWORD src1_sel:BYTE_0
	v_and_or_b32 v4, v5, s5, v4
	v_and_b32_e32 v6, 4, v6
	v_and_b32_e32 v7, 24, v7
	v_and_b32_e32 v2, 32, v2
	v_bfe_i32 v0, v0, 0, 16
	v_or3_b32 v4, v4, v6, v7
	v_add_lshl_u32 v0, v2, v0, 1
	s_movk_i32 s12, 0x300
	v_lshl_add_u32 v64, v4, 9, v0
	v_mad_u64_u32 v[66:67], s[8:9], v5, s12, v[0:1]
	v_bfe_i32 v0, v8, 27, 1
	v_lshrrev_b32_e32 v0, 22, v0
	v_add_u32_e32 v0, v1, v0
	v_and_b32_e32 v0, 0xfffffc00, v0
	v_sub_u32_e32 v0, v1, v0
	v_lshrrev_b32_e32 v1, 4, v0
	v_ashrrev_i32_e32 v4, 31, v8
	v_bitop3_b32 v0, v1, v0, 32 bitop3:0x6c
	v_lshrrev_b32_e32 v4, 26, v4
	v_ashrrev_i32_e32 v1, 31, v0
	v_add_u32_e32 v4, v8, v4
	v_readlane_b32 s0, v255, 15
	v_lshrrev_b32_e32 v1, 26, v1
	v_ashrrev_i32_e32 v4, 6, v4
	s_addc_u32 s71, s0, s1
	s_ashr_i32 s10, s4, 6
	v_add_u32_e32 v1, v0, v1
	v_lshlrev_b32_e32 v5, 3, v4
	s_ashr_i32 s11, s4, 8
	s_lshl_b32 s28, s10, 10
	v_ashrrev_i32_e32 v2, 6, v1
	v_and_b32_e32 v5, -16, v5
	v_and_b32_e32 v1, 0xc0, v1
	s_add_u32 s0, s30, 0x18000
	v_add_u32_e32 v5, v2, v5
	v_sub_u32_e32 v0, v0, v1
	s_addc_u32 s1, s31, 0
	v_and_b32_e32 v2, 3, v2
	v_lshrrev_b32_e32 v6, 2, v5
	v_lshlrev_b32_e32 v7, 1, v5
	v_lshlrev_b32_e32 v4, 5, v4
	v_ashrrev_i16_sdwa v0, v3, sext(v0) dst_sel:DWORD dst_unused:UNUSED_PAD src0_sel:DWORD src1_sel:BYTE_0
	s_add_u32 s6, s70, 0x10000
	v_and_or_b32 v2, v5, s5, v2
	v_and_b32_e32 v6, 4, v6
	v_and_b32_e32 v7, 24, v7
	v_and_b32_e32 v4, 32, v4
	v_bfe_i32 v0, v0, 0, 16
	s_addc_u32 s7, s71, 0
	v_or3_b32 v2, v2, v6, v7
	v_add_lshl_u32 v0, v4, v0, 1
	s_add_i32 s17, s28, 0
	v_lshl_add_u32 v68, v2, 9, v0
	s_nop 0
	s_add_i32 m0, s17, 0x10000
	s_add_i32 s20, s17, 0x14000
	global_load_lds_dwordx4 v68, s[70:71]
	s_add_i32 m0, s17, 0x12000
	s_add_i32 s21, s17, 0x16000
	global_load_lds_dwordx4 v64, s[70:71]
	s_mov_b32 m0, s20
	v_mad_u64_u32 v[70:71], s[8:9], v5, s12, v[0:1]
	global_load_lds_dwordx4 v68, s[6:7]
	s_mov_b32 m0, s21
	s_add_i32 s34, s17, 0x2000
	global_load_lds_dwordx4 v64, s[6:7]
	s_mov_b32 m0, s17
	s_add_i32 s35, s17, 0x4000
	global_load_lds_dwordx4 v70, s[30:31]
	s_mov_b32 m0, s34
	s_add_i32 s44, s17, 0x6000
	global_load_lds_dwordx4 v66, s[30:31]
	s_mov_b32 m0, s35
	v_mov_b32_e32 v73, 0
	global_load_lds_dwordx4 v70, s[0:1]
	s_mov_b32 m0, s44
	v_mov_b32_e32 v69, v73
	global_load_lds_dwordx4 v66, s[0:1]
	v_mov_b32_e32 v65, v73
	v_mov_b32_e32 v71, v73
	v_mov_b32_e32 v67, v73
	s_cmp_eq_u32 s11, 1
	s_mov_b64 s[14:15], s[96:97]
	s_mov_b32 s5, 0
	v_lshl_add_u64 v[6:7], s[70:71], 0, v[68:69]
	v_lshl_add_u64 v[4:5], s[70:71], 0, v[64:65]
	v_lshl_add_u64 v[0:1], s[30:31], 0, v[70:71]
	s_cselect_b64 s[6:7], -1, 0
	s_cmp_lg_u32 s11, 1
	v_lshl_add_u64 v[2:3], s[30:31], 0, v[66:67]
	s_cbranch_scc1 .LBB0_605
	s_barrier

; #define LAS __attribute__((address_space(3)))
; __host__ __device__ __forceinline__ size_t ux_off(int m, int ch) { return ((size_t)((ch >> 4) * UXROWS + (m >> 4)) * UXR + (m & 15)) * 16 + (ch & 15); }
; #define PG8_WAIT_V(n) asm volatile("s_waitcnt vmcnt(" #n ")" ::: "memory")
; #define PG8_BAR __builtin_amdgcn_s_barrier()
; #define TIDS() const int tid = fresh_tid(), lane = tid & 63, wave = __builtin_amdgcn_readfirstlane(tid >> 6); (void)lane; (void)wave
; template <class Epi, class Sched>
; __device__ __forceinline__ void gemm_phase(LAS unsigned char* lds, const Gemm g, const Sched& S, const Epi& E) {
;     ...
;     PG8_WAIT_V(0);
;     PG8_BAR;
; __global__ void __launch_bounds__(NTHR, 2) hymba_fwd(Params P) {
;     ...
;     __syncthreads();
;     for (int it = blk; it < NB * NG; it += G) {
;         TIDS();
;         const int b = it >> 5, g = it & 31;
;         LAS f32x2* XS = (LAS f32x2*)lds;
;         LAS float* US = (LAS float*)(lds + 33280);
;         LAS float* CR = (LAS float*)(lds + 37376);
;         LAS float* CI = (LAS float*)(lds + 41536);
;         for (int i = tid; i < 1024; i += NTHR) { const int t = i >> 4, p = i & 15, s = b * 64 + t; US[i] = bf2f(UX[ux_off(PT + s, g * 16 + p)]);
;             CR[(i >> 6) * 65 + (i & 63)] = P.c_re[g * 1024 + i]; CI[(i >> 6) * 65 + (i & 63)] = P.c_im[g * 1024 + i]; }
.LBB0_615:
	s_nop 0
	s_mov_b64 s[96:97], s[14:15]
	s_barrier
.LBB0_616:
	v_readlane_b32 s6, v255, 18
	v_readlane_b32 s7, v255, 19
	s_add_u32 s4, s92, 0x2f500000
	s_addc_u32 s5, s93, 0
	v_cndmask_b32_e64 v0, 0, 1, s[6:7]
	v_cmp_ne_u32_e64 s[0:1], 1, v0
	s_andn2_b64 vcc, exec, s[6:7]
	s_nop 0
	s_barrier
	s_cbranch_vccnz .LBB0_633
	v_mov_b32_e32 v33, 0
	s_mov_b32 s7, 0
	s_add_i32 s17, 0, 0x8200
	s_mov_b64 s[8:9], 0x800
	s_movk_i32 s20, 0x208
	s_add_i32 s21, 0, 0x9200
	s_movk_i32 s28, 0x7fff
	s_mov_b32 s29, s2
	s_mov_b32 s34, s2

; #define PG8_STAGE(bufoff, gbase, voff) do { _Pragma("unroll") for (int _i = 0; _i < 2; ++_i) \
;         __builtin_amdgcn_global_load_lds((const unsigned*)((const char*)(gbase) + (voff)[_i]), (LAS unsigned*)(lds + (bufoff) + ldsw + _i * 8192), 16, 0, 0); } while (0)
; #define PG8_WAIT_V(n) asm volatile("s_waitcnt vmcnt(" #n ")" ::: "memory")
; #define PG8_BAR __builtin_amdgcn_s_barrier()
; template <class Epi, class Sched>
; __device__ __forceinline__ void gemm_phase(LAS unsigned char* lds, const Gemm g, const Sched& S, const Epi& E) {
;     ...
;     for (int i = 0; i < 2; ++i) { int R, C; stage_rc(tid * 16 + i * 8192, R, C); const int Rb = Epi::PERM ? ((R & ~31) + perm32(R & 31)) : R;
;         voffA[i] = (unsigned)R * g.lda + (g.aplane ? (unsigned)(C >> 4) * g.aplane + (unsigned)((C & 15) * 2) : (unsigned)(C * 2)); voffB[i] = (unsigned)Rb * g.ldb + (unsigned)(C * 2); }
;     const size_t kstepA = g.kstepA, kstepB = g.kstepB;
;     const size_t hstepA = (size_t)HALF * g.lda, hstepB = (size_t)HALF * g.ldb;
;     const unsigned ldsw = (unsigned)wid * 1024u;
;     const int aoff = lds_byte(wr * 64 + fr, fq * 8), boff = lds_byte(wc * 32 + fr, fq * 8);
;     ...
;     Unit cur, nxt; int ui = 0;
;     if (!S.next(0, cur)) return;
;     f32x4 acc[2][2][4][2];
; #pragma unroll
;     for (int a = 0; a < 2; ++a)
; #pragma unroll
;         for (int b = 0; b < 2; ++b)
; #pragma unroll
;             for (int m = 0; m < 4; ++m)
; #pragma unroll
;                 for (int n = 0; n < 2; ++n) acc[a][b][m][n] = (f32x4){0.f, 0.f, 0.f, 0.f};
;     bf16x8 At[4][2], B0[2][2], B1[2][2];
;     const char* cA = cur.a; const char* cB = cur.b;
;     PG8_WAIT_V(0);
;     PG8_STAGE(PG8_SB(0, 0), cB, voffB); PG8_STAGE(PG8_SB(0, 1), cB + hstepB, voffB); PG8_STAGE(PG8_SA(0, 0), cA, voffA); PG8_STAGE(PG8_SA(0, 1), cA + hstepA, voffA);
;     if (wr == 1) PG8_BAR;
;     PG8_WAIT_V(2); PG8_BAR;
;     PG8_STAGE(PG8_SB(1, 0), cB + kstepB, voffB); PG8_STAGE(PG8_SA(1, 0), cA + kstepA, voffA); PG8_STAGE(PG8_SB(1, 1), cB + hstepB + kstepB, voffB);
; __global__ void __launch_bounds__(NTHR, 2) hymba_fwd(Params P) {
;     ...
;         pg8::Gemm g{UXR * 32, 384 * 2, 128, 128, 6, 0}; pg8::S5Order S{G, blk, (const char*)UX, (const char*)W2, (size_t)256 * 384 * 2};
;         EpiY E{YS};
;         pg8::gemm_phase<EpiY, pg8::S5Order>(lds, g, S, E);
.LBB0_894:
	s_and_b32 s16, s2, 31
	s_lshr_b32 s88, s2, 5
	s_lshl_b32 s88, s88, 1
	s_mul_i32 s0, s16, 0x306000
	s_mul_i32 s1, s88, 0x30000
	s_add_u32 s30, s22, s0
	s_addc_u32 s31, s23, 0
	s_add_u32 s30, s30, s1
	s_addc_u32 s31, s31, 0
	v_readlane_b32 s0, v255, 20
	s_add_u32 s4, s92, 0x2b400000
	v_mov_b32_e32 v8, v208
	v_readlane_b32 s1, v255, 21
	v_readlane_b32 s66, v255, 24
	s_addc_u32 s5, s93, 0
	s_and_b64 vcc, exec, s[0:1]
	v_readfirstlane_b32 s10, v8
	v_readlane_b32 s64, v255, 23
	v_readlane_b32 s67, v255, 25
	s_cbranch_vccz .LBB0_908
	v_lshlrev_b32_e32 v1, 4, v8
	v_add_u32_e32 v0, 0x2000, v1
	v_ashrrev_i32_e32 v2, 31, v0
	v_lshrrev_b32_e32 v2, 22, v2
	v_add_u32_e32 v2, v0, v2
	v_ashrrev_i32_e32 v2, 10, v2
	v_mul_i32_i24_e32 v3, 0x400, v2
	v_sub_u32_e32 v0, v0, v3
	v_lshrrev_b32_e32 v3, 4, v0
	v_bitop3_b32 v0, v3, v0, 32 bitop3:0x6c
	v_ashrrev_i32_e32 v3, 31, v0
	v_lshrrev_b32_e32 v3, 26, v3
	v_add_u32_e32 v3, v0, v3
	v_lshlrev_b32_e32 v5, 3, v2
	v_ashrrev_i32_e32 v4, 6, v3
	v_and_b32_e32 v5, -16, v5
	v_and_b32_e32 v3, 0xc0, v3
	v_add_u32_e32 v5, v4, v5
	v_sub_u32_e32 v0, v0, v3
	v_mov_b32_e32 v3, 1
	v_and_b32_e32 v4, 3, v4
	s_mov_b32 s13, 0xffffe0
	v_lshrrev_b32_e32 v6, 2, v5
	v_lshlrev_b32_e32 v7, 1, v5
	v_lshlrev_b32_e32 v2, 5, v2
	v_ashrrev_i16_sdwa v0, v3, sext(v0) dst_sel:DWORD dst_unused:UNUSED_PAD src0_sel:DWORD src1_sel:BYTE_0
	v_and_or_b32 v4, v5, s13, v4
	v_and_b32_e32 v6, 4, v6
	v_and_b32_e32 v7, 24, v7
	v_and_b32_e32 v2, 32, v2
	v_bfe_i32 v0, v0, 0, 16
	v_or3_b32 v4, v4, v6, v7
	v_add_lshl_u32 v0, v2, v0, 1
	s_movk_i32 s20, 0x300
	v_mad_u32_u24 v128, v4, s20, v0
	v_mad_u64_u32 v[130:131], s[8:9], v5, s20, v[0:1]
	v_bfe_i32 v0, v8, 27, 1
	v_lshrrev_b32_e32 v0, 22, v0
	v_add_u32_e32 v0, v1, v0
	v_and_b32_e32 v0, 0xfffffc00, v0
	v_sub_u32_e32 v0, v1, v0
	v_lshrrev_b32_e32 v1, 4, v0
	v_ashrrev_i32_e32 v4, 31, v8
	v_bitop3_b32 v0, v1, v0, 32 bitop3:0x6c
	v_lshrrev_b32_e32 v4, 26, v4
	v_ashrrev_i32_e32 v1, 31, v0
	v_add_u32_e32 v4, v8, v4
	s_mul_i32 s1, s16, 0x30000
	v_readlane_b32 s14, v255, 12
	v_lshrrev_b32_e32 v1, 26, v1
	v_ashrrev_i32_e32 v4, 6, v4
	s_mul_hi_i32 s0, s16, 0x30000
	s_add_u32 s42, s14, s1
	v_readlane_b32 s15, v255, 13
	v_add_u32_e32 v1, v0, v1
	v_lshlrev_b32_e32 v5, 3, v4
	s_addc_u32 s43, s15, s0
	s_ashr_i32 s12, s10, 6
	v_ashrrev_i32_e32 v2, 6, v1
	v_and_b32_e32 v5, -16, v5
	v_and_b32_e32 v1, 0xc0, v1
	s_ashr_i32 s11, s10, 8
	s_lshl_b32 s17, s12, 10
	v_add_u32_e32 v5, v2, v5
	v_sub_u32_e32 v0, v0, v1
	s_add_u32 s0, s30, 0x18000
	v_and_b32_e32 v2, 3, v2
	v_lshrrev_b32_e32 v6, 2, v5
	v_lshlrev_b32_e32 v7, 1, v5
	v_lshlrev_b32_e32 v4, 5, v4
	v_ashrrev_i16_sdwa v0, v3, sext(v0) dst_sel:DWORD dst_unused:UNUSED_PAD src0_sel:DWORD src1_sel:BYTE_0
	s_addc_u32 s1, s31, 0
	v_and_or_b32 v2, v5, s13, v2
	v_and_b32_e32 v6, 4, v6
	v_and_b32_e32 v7, 24, v7
	v_and_b32_e32 v4, 32, v4
	v_bfe_i32 v0, v0, 0, 16
	s_add_u32 s6, s42, 0x18000
	v_or3_b32 v2, v2, v6, v7
	v_add_lshl_u32 v0, v4, v0, 1
	s_addc_u32 s7, s43, 0
	v_mad_u32_u24 v132, v2, s20, v0
	v_mad_u64_u32 v[134:135], s[8:9], v5, s20, v[0:1]
	s_add_i32 s20, s17, 0
	s_nop 0
	s_add_i32 m0, s20, 0x10000
	s_add_i32 s21, s20, 0x2000
	global_load_lds_dwordx4 v132, s[42:43]
	s_add_i32 m0, s20, 0x12000
	s_add_i32 s44, s20, 0x4000
	global_load_lds_dwordx4 v128, s[42:43]
	s_add_i32 m0, s20, 0x14000
	s_add_i32 s45, s20, 0x6000
	global_load_lds_dwordx4 v132, s[6:7]
	s_add_i32 m0, s20, 0x16000
	v_mov_b32_e32 v137, 0
	global_load_lds_dwordx4 v128, s[6:7]
	s_mov_b32 m0, s20
	v_mov_b32_e32 v133, v137
	global_load_lds_dwordx4 v134, s[30:31]
	s_mov_b32 m0, s21
	v_mov_b32_e32 v129, v137
	global_load_lds_dwordx4 v130, s[30:31]
	s_mov_b32 m0, s44
	v_mov_b32_e32 v135, v137
	global_load_lds_dwordx4 v134, s[0:1]
	s_mov_b32 m0, s45
	v_mov_b32_e32 v131, v137
	global_load_lds_dwordx4 v130, s[0:1]
	s_cmp_eq_u32 s11, 1
	v_lshl_add_u64 v[6:7], s[42:43], 0, v[132:133]
	v_lshl_add_u64 v[4:5], s[42:43], 0, v[128:129]
	v_lshl_add_u64 v[0:1], s[30:31], 0, v[134:135]
	s_cselect_b64 s[6:7], -1, 0
	s_cmp_lg_u32 s11, 1
	v_lshl_add_u64 v[2:3], s[30:31], 0, v[130:131]
	s_cbranch_scc1 .LBB0_897
	s_barrier

; #define PG8_WAIT_V(n) asm volatile("s_waitcnt vmcnt(" #n ")" ::: "memory")
; #define PG8_BAR __builtin_amdgcn_s_barrier()
;     __device__ bool next(int i, Unit& u) const {
;         const long L = (long)i * G + c; if (L >= nwg) return false;
;         int wgid = (int)L; { const int q = nwg / NXCD, r = nwg % NXCD, xcd = wgid % NXCD, off = wgid / NXCD; wgid = (xcd < r ? xcd * (q + 1) : r * (q + 1) + (xcd - r) * q) + off; }
;         const int nig = WGM * nN, gid = wgid / nig, fm = gid * WGM, gsz = (nM - fm) < WGM ? (nM - fm) : WGM;
;         u.pm = fm + ((wgid % nig) % gsz); u.pn = (wgid % nig) / gsz; u.g = 0; u.a = A + (size_t)u.pm * ta; u.b = B + (size_t)u.pn * tb; return true;
; template <class Epi, class Sched>
; __device__ __forceinline__ void gemm_phase(LAS unsigned char* lds, const Gemm g, const Sched& S, const Epi& E) {
;     ...
;     for (int i = 0; i < 2; ++i) { int R, C; stage_rc(tid * 16 + i * 8192, R, C); const int Rb = Epi::PERM ? ((R & ~31) + perm32(R & 31)) : R;
;         voffA[i] = (unsigned)R * g.lda + (g.aplane ? (unsigned)(C >> 4) * g.aplane + (unsigned)((C & 15) * 2) : (unsigned)(C * 2)); voffB[i] = (unsigned)Rb * g.ldb + (unsigned)(C * 2); }
;     const size_t kstepA = g.kstepA, kstepB = g.kstepB;
;     const size_t hstepA = (size_t)HALF * g.lda, hstepB = (size_t)HALF * g.ldb;
;     const unsigned ldsw = (unsigned)wid * 1024u;
;     const int aoff = lds_byte(wr * 64 + fr, fq * 8), boff = lds_byte(wc * 32 + fr, fq * 8);
;     ...
;     Unit cur, nxt; int ui = 0;
;     if (!S.next(0, cur)) return;
;     f32x4 acc[2][2][4][2];
; #pragma unroll
;     for (int a = 0; a < 2; ++a)
; #pragma unroll
;         for (int b = 0; b < 2; ++b)
; #pragma unroll
;             for (int m = 0; m < 4; ++m)
; #pragma unroll
;                 for (int n = 0; n < 2; ++n) acc[a][b][m][n] = (f32x4){0.f, 0.f, 0.f, 0.f};
;     bf16x8 At[4][2], B0[2][2], B1[2][2];
;     const char* cA = cur.a; const char* cB = cur.b;
;     PG8_WAIT_V(0);
;     PG8_STAGE(PG8_SB(0, 0), cB, voffB); PG8_STAGE(PG8_SB(0, 1), cB + hstepB, voffB); PG8_STAGE(PG8_SA(0, 0), cA, voffA); PG8_STAGE(PG8_SA(0, 1), cA + hstepA, voffA);
;     if (wr == 1) PG8_BAR;
;     PG8_WAIT_V(2); PG8_BAR;
;     PG8_STAGE(PG8_SB(1, 0), cB + kstepB, voffB); PG8_STAGE(PG8_SA(1, 0), cA + kstepA, voffA); PG8_STAGE(PG8_SB(1, 1), cB + hstepB + kstepB, voffB);
.Lmy_glu_skip:
	s_and_b64 vcc, exec, s[6:7]
	v_readfirstlane_b32 s1, v4
	s_cbranch_vccz .LBB0_981
	v_lshlrev_b32_e32 v0, 4, v4
	v_add_u32_e32 v1, 0x2000, v0
	v_ashrrev_i32_e32 v2, 31, v1
	v_lshrrev_b32_e32 v2, 22, v2
	v_add_u32_e32 v2, v1, v2
	v_ashrrev_i32_e32 v5, 10, v2
	v_mul_i32_i24_e32 v2, 0x400, v5
	v_sub_u32_e32 v1, v1, v2
	v_lshrrev_b32_e32 v2, 4, v1
	v_bitop3_b32 v1, v2, v1, 32 bitop3:0x6c
	v_ashrrev_i32_e32 v2, 31, v1
	v_lshrrev_b32_e32 v2, 26, v2
	v_add_u32_e32 v2, v1, v2
	v_lshlrev_b32_e32 v3, 3, v5
	v_ashrrev_i32_e32 v6, 6, v2
	v_and_b32_e32 v3, -16, v3
	v_add_u32_e32 v3, v6, v3
	v_and_b32_e32 v7, 3, v6
	s_mov_b32 s0, 0x3fffe0
	v_lshrrev_b32_e32 v8, 2, v3
	v_lshlrev_b32_e32 v9, 1, v3
	v_and_or_b32 v7, v3, s0, v7
	v_and_b32_e32 v8, 4, v8
	v_and_b32_e32 v9, 24, v9
	v_and_b32_e32 v2, 0xc0, v2
	v_or3_b32 v7, v7, v8, v9
	v_lshlrev_b32_e32 v8, 5, v5
	v_sub_u32_e32 v1, v1, v2
	v_mov_b32_e32 v2, 1
	v_and_b32_e32 v8, 32, v8
	v_ashrrev_i16_sdwa v1, v2, sext(v1) dst_sel:DWORD dst_unused:UNUSED_PAD src0_sel:DWORD src1_sel:BYTE_0
	v_add_u32_sdwa v1, v8, sext(v1) dst_sel:DWORD dst_unused:UNUSED_PAD src0_sel:DWORD src1_sel:WORD_0
	v_lshlrev_b32_e32 v8, 1, v1
	v_lshlrev_b32_e32 v1, 17, v1
	v_lshl_add_u32 v156, v7, 10, v8
	v_and_b32_e32 v7, 30, v8
	v_and_b32_e32 v8, 0xffe00000, v1
	v_bfe_i32 v1, v4, 27, 1
	v_lshrrev_b32_e32 v1, 22, v1
	v_add_u32_e32 v1, v0, v1
	v_and_b32_e32 v1, 0xfffffc00, v1
	v_lshl_or_b32 v3, v3, 5, v7
	v_sub_u32_e32 v0, v0, v1
	v_add_u32_e32 v158, v3, v8
	v_lshrrev_b32_e32 v1, 4, v0
	v_ashrrev_i32_e32 v3, 31, v4
	v_bitop3_b32 v0, v1, v0, 32 bitop3:0x6c
	v_lshrrev_b32_e32 v3, 26, v3
	v_ashrrev_i32_e32 v1, 31, v0
	v_add_u32_e32 v3, v4, v3
	v_lshrrev_b32_e32 v1, 26, v1
	v_ashrrev_i32_e32 v10, 6, v3
	v_add_u32_e32 v1, v0, v1
	v_lshlrev_b32_e32 v3, 3, v10
	s_ashr_i32 s8, s1, 6
	v_ashrrev_i32_e32 v9, 6, v1
	v_and_b32_e32 v3, -16, v3
	s_ashr_i32 s10, s1, 8
	s_lshl_b32 s20, s8, 10
	v_add_u32_e32 v3, v9, v3
	v_and_b32_e32 v11, 3, v9
	s_lshl_b32 s9, s64, 6
	v_and_or_b32 v11, v3, s0, v11
	s_mul_i32 s0, s64, 0x41
	s_and_b64 s[6:7], s[66:67], exec
	s_cselect_b32 s0, s0, s9
	v_readlane_b32 s6, v255, 22
	s_add_i32 s0, s0, s6
	s_ashr_i32 s6, s0, 31
	s_lshr_b32 s6, s6, 28
	s_add_i32 s6, s0, s6
	s_ashr_i32 s7, s6, 4
	s_and_b32 s6, s6, 0xfff0
	s_sub_i32 s6, s0, s6
	s_bfe_i32 s0, s6, 0x80000
	s_bfe_u32 s0, s0, 0x3000c
	s_add_i32 s9, s6, s0
	s_bfe_i32 s0, s9, 0x80000
	s_and_b32 s9, s9, 0xf8
	s_sub_i32 s6, s6, s9
	s_lshl_b32 s7, s7, 3
	s_sext_i32_i8 s6, s6
	s_add_i32 s24, s7, s6
	s_sext_i32_i16 s0, s0
	s_ashr_i32 s25, s24, 31
	v_lshrrev_b32_e32 v12, 2, v3
	v_lshlrev_b32_e32 v13, 1, v3
	s_lshr_b32 s0, s0, 3
	s_lshl_b64 s[6:7], s[24:25], 13
	v_and_b32_e32 v12, 4, v12
	v_and_b32_e32 v13, 24, v13
	v_and_b32_e32 v1, 0xc0, v1
	s_add_u32 s26, s4, s6
	v_or3_b32 v11, v11, v12, v13
	v_lshlrev_b32_e32 v12, 5, v10
	v_sub_u32_e32 v0, v0, v1
	s_addc_u32 s27, s5, s7
	s_bfe_i64 s[6:7], s[0:1], 0x100000
	v_and_b32_e32 v12, 32, v12
	v_ashrrev_i16_sdwa v0, v2, sext(v0) dst_sel:DWORD dst_unused:UNUSED_PAD src0_sel:DWORD src1_sel:BYTE_0
	s_lshl_b64 s[6:7], s[6:7], 18
	v_readlane_b32 s12, v255, 16
	v_add_u32_sdwa v0, v12, sext(v0) dst_sel:DWORD dst_unused:UNUSED_PAD src0_sel:DWORD src1_sel:WORD_0
	v_readlane_b32 s13, v255, 17
	s_add_u32 s28, s12, s6
	v_lshlrev_b32_e32 v1, 1, v0
	s_addc_u32 s29, s13, s7
	s_add_i32 s21, s20, 0
	v_lshl_add_u32 v160, v11, 10, v1
	s_nop 0
	s_add_i32 m0, s21, 0x10000
	v_and_b32_e32 v11, 30, v1
	global_load_lds_dwordx4 v160, s[28:29]
	s_add_i32 m0, s21, 0x12000
	s_add_u32 s6, s28, 0x20000
	v_lshlrev_b32_e32 v0, 17, v0
	global_load_lds_dwordx4 v156, s[28:29]
	s_addc_u32 s7, s29, 0
	s_add_i32 m0, s21, 0x14000
	v_lshl_or_b32 v1, v3, 5, v11
	v_and_b32_e32 v12, 0xffe00000, v0
	global_load_lds_dwordx4 v160, s[6:7]
	s_add_i32 m0, s21, 0x16000
	s_add_i32 s25, s21, 0x2000
	v_add_u32_e32 v162, v1, v12
	global_load_lds_dwordx4 v156, s[6:7]
	s_mov_b32 m0, s21
	s_add_u32 s6, s26, 0x1000
	global_load_lds_dwordx4 v162, s[26:27]
	s_mov_b32 m0, s25
	s_addc_u32 s7, s27, 0
	s_add_i32 s42, s21, 0x4000
	global_load_lds_dwordx4 v158, s[26:27]
	s_mov_b32 m0, s42
	s_add_i32 s43, s21, 0x6000
	global_load_lds_dwordx4 v162, s[6:7]
	s_mov_b32 m0, s43
	v_mov_b32_e32 v161, 0
	global_load_lds_dwordx4 v158, s[6:7]
	v_mov_b32_e32 v157, v161
	s_cmp_eq_u32 s10, 1
	s_mov_b32 s44, 0
	v_lshl_add_u64 v[2:3], s[28:29], 0, v[160:161]
	v_lshl_add_u64 v[0:1], s[28:29], 0, v[156:157]
	v_mov_b32_e32 v163, v161
	s_cselect_b64 s[6:7], -1, 0
	s_cmp_lg_u32 s10, 1
	v_mov_b32_e32 v159, v161
	s_cbranch_scc1 .LBB0_964
	s_barrier

; #define PG8_STAGE(bufoff, gbase, voff) do { _Pragma("unroll") for (int _i = 0; _i < 2; ++_i) \
;         __builtin_amdgcn_global_load_lds((const unsigned*)((const char*)(gbase) + (voff)[_i]), (LAS unsigned*)(lds + (bufoff) + ldsw + _i * 8192), 16, 0, 0); } while (0)
; #define PG8_WAIT_V(n) asm volatile("s_waitcnt vmcnt(" #n ")" ::: "memory")
; #define PG8_BAR __builtin_amdgcn_s_barrier()
; #define MOD WSP(float, WS_MOD)
; template <class Epi, class Sched>
; __device__ __forceinline__ void gemm_phase(LAS unsigned char* lds, const Gemm g, const Sched& S, const Epi& E) {
;     ...
;     for (int i = 0; i < 2; ++i) { int R, C; stage_rc(tid * 16 + i * 8192, R, C); const int Rb = Epi::PERM ? ((R & ~31) + perm32(R & 31)) : R;
;         voffA[i] = (unsigned)R * g.lda + (g.aplane ? (unsigned)(C >> 4) * g.aplane + (unsigned)((C & 15) * 2) : (unsigned)(C * 2)); voffB[i] = (unsigned)Rb * g.ldb + (unsigned)(C * 2); }
;     const size_t kstepA = g.kstepA, kstepB = g.kstepB;
;     const size_t hstepA = (size_t)HALF * g.lda, hstepB = (size_t)HALF * g.ldb;
;     const unsigned ldsw = (unsigned)wid * 1024u;
;     const int aoff = lds_byte(wr * 64 + fr, fq * 8), boff = lds_byte(wc * 32 + fr, fq * 8);
;     ...
;     Unit cur, nxt; int ui = 0;
;     if (!S.next(0, cur)) return;
;     f32x4 acc[2][2][4][2];
; #pragma unroll
;     for (int a = 0; a < 2; ++a)
; #pragma unroll
;         for (int b = 0; b < 2; ++b)
; #pragma unroll
;             for (int m = 0; m < 4; ++m)
; #pragma unroll
;                 for (int n = 0; n < 2; ++n) acc[a][b][m][n] = (f32x4){0.f, 0.f, 0.f, 0.f};
;     bf16x8 At[4][2], B0[2][2], B1[2][2];
;     const char* cA = cur.a; const char* cB = cur.b;
;     PG8_WAIT_V(0);
;     PG8_STAGE(PG8_SB(0, 0), cB, voffB); PG8_STAGE(PG8_SB(0, 1), cB + hstepB, voffB); PG8_STAGE(PG8_SA(0, 0), cA, voffA); PG8_STAGE(PG8_SA(0, 1), cA + hstepA, voffA);
;     if (wr == 1) PG8_BAR;
;     PG8_WAIT_V(2); PG8_BAR;
;     PG8_STAGE(PG8_SB(1, 0), cB + kstepB, voffB); PG8_STAGE(PG8_SA(1, 0), cA + kstepA, voffA); PG8_STAGE(PG8_SB(1, 1), cB + hstepB + kstepB, voffB);
; __global__ void __launch_bounds__(NTHR, 2) hymba_fwd(Params P) {
;     ...
;         pg8::Gemm g{DM * 2, DM * 2, 128, 128, DM / 64, 0}; pg8::StaticOrder S; S.init(PT, DM, G, blk, MX, WOUT, DM * 2, DM * 2);
;         EpiOut E{P.x_prompt, P.x_sample, MOD, out + O_YP, out + O_YS};
;         pg8::gemm_phase<EpiOut, pg8::StaticOrder>(lds, g, S, E);
.Lmy_op_done:
	v_readlane_b32 s64, v255, 23
	v_readlane_b32 s66, v255, 24
	v_readlane_b32 s67, v255, 25
	s_cmpk_lt_i32 s2, 0x400
	s_nop 0
	v_readfirstlane_b32 s1, v208
	s_cbranch_scc0 .LBB0_1054
	v_lshlrev_b32_e32 v0, 4, v208
	v_add_u32_e32 v1, 0x2000, v0
	v_ashrrev_i32_e32 v2, 31, v1
	v_lshrrev_b32_e32 v2, 22, v2
	v_add_u32_e32 v2, v1, v2
	v_ashrrev_i32_e32 v8, 10, v2
	v_mul_i32_i24_e32 v3, 0x400, v8
	v_sub_u32_e32 v1, v1, v3
	v_lshrrev_b32_e32 v3, 4, v1
	v_bitop3_b32 v1, v3, v1, 32 bitop3:0x6c
	v_ashrrev_i32_e32 v3, 31, v1
	v_lshrrev_b32_e32 v3, 26, v3
	v_add_u32_e32 v3, v1, v3
	s_ashr_i32 s6, s1, 6
	v_ashrrev_i32_e32 v9, 6, v3
	v_and_b32_e32 v3, 0xc0, v3
	s_ashr_i32 s7, s1, 8
	s_lshl_b32 s46, s6, 10
	v_sub_u32_e32 v1, v1, v3
	v_mov_b32_e32 v3, 1
	s_lshl_b32 s8, s64, 7
	v_lshlrev_b32_e32 v2, 5, v8
	v_ashrrev_i16_sdwa v1, v3, sext(v1) dst_sel:DWORD dst_unused:UNUSED_PAD src0_sel:DWORD src1_sel:BYTE_0
	s_mul_i32 s0, s64, 0x81
	s_and_b64 s[4:5], s[66:67], exec
	v_and_b32_e32 v2, 32, v2
	v_bfe_i32 v10, v1, 0, 16
	s_cselect_b32 s0, s0, s8
	v_readlane_b32 s4, v255, 22
	v_add_u32_e32 v1, v2, v10
	v_lshlrev_b32_e32 v2, 3, v8
	s_add_i32 s0, s0, s4
	v_and_b32_e32 v2, 0x1ffff0, v2
	s_ashr_i32 s4, s0, 31
	v_add_lshl_u32 v2, v9, v2, 11
	s_lshr_b32 s4, s4, 27
	v_lshl_add_u32 v144, v1, 1, v2
	v_bfe_i32 v2, v208, 27, 1
	s_add_i32 s4, s0, s4
	v_lshrrev_b32_e32 v2, 22, v2
	s_ashr_i32 s5, s4, 5
	s_and_b32 s4, s4, 0xffe0
	v_add_u32_e32 v2, v0, v2
	s_sub_i32 s4, s0, s4
	v_and_b32_e32 v2, 0xfffffc00, v2
	s_bfe_i32 s0, s4, 0x80000
	v_sub_u32_e32 v0, v0, v2
	s_bfe_u32 s0, s0, 0x3000c
	v_lshrrev_b32_e32 v2, 4, v0
	s_add_i32 s8, s4, s0
	v_bitop3_b32 v0, v2, v0, 32 bitop3:0x6c
	s_bfe_i32 s0, s8, 0x80000
	s_and_b32 s8, s8, 0xf8
	v_ashrrev_i32_e32 v2, 31, v0
	s_sub_i32 s4, s4, s8
	v_ashrrev_i32_e32 v1, 31, v208
	v_lshrrev_b32_e32 v2, 26, v2
	s_lshl_b32 s5, s5, 3
	s_sext_i32_i8 s4, s4
	v_lshrrev_b32_e32 v1, 26, v1
	v_add_u32_e32 v2, v0, v2
	s_add_i32 s34, s5, s4
	v_add_u32_e32 v1, v208, v1
	v_ashrrev_i32_e32 v12, 6, v2
	v_and_b32_e32 v2, 0xc0, v2
	s_sext_i32_i16 s0, s0
	s_ashr_i32 s35, s34, 31
	v_ashrrev_i32_e32 v11, 6, v1
	v_sub_u32_e32 v0, v0, v2
	s_lshr_b32 s0, s0, 3
	s_lshl_b64 s[4:5], s[34:35], 19
	v_lshlrev_b32_e32 v1, 5, v11
	v_ashrrev_i16_sdwa v0, v3, sext(v0) dst_sel:DWORD dst_unused:UNUSED_PAD src0_sel:DWORD src1_sel:BYTE_0
	s_add_u32 s38, s40, s4
	v_and_b32_e32 v1, 32, v1
	v_bfe_i32 v13, v0, 0, 16
	s_addc_u32 s39, s41, s5
	s_bfe_i64 s[4:5], s[0:1], 0x100000
	v_add_u32_e32 v0, v1, v13
	v_lshlrev_b32_e32 v1, 3, v11
	s_lshl_b64 s[4:5], s[4:5], 19
	v_and_b32_e32 v1, 0x1ffff0, v1
	s_add_u32 s42, s96, s4
	v_add_lshl_u32 v1, v12, v1, 11
	s_addc_u32 s43, s97, s5
	s_add_i32 s35, s46, 0
	v_lshl_add_u32 v146, v0, 1, v1
	s_nop 0
	s_add_i32 m0, s35, 0x10000
	v_mov_b32_e32 v147, 0
	global_load_lds_dwordx4 v146, s[42:43]
	s_add_i32 m0, s35, 0x12000
	s_add_u32 s4, s42, 0x40000
	global_load_lds_dwordx4 v144, s[42:43]
	s_addc_u32 s5, s43, 0
	s_add_i32 m0, s35, 0x14000
	s_add_i32 s47, s35, 0x2000
	global_load_lds_dwordx4 v146, s[4:5]
	s_add_i32 m0, s35, 0x16000
	v_mov_b32_e32 v145, v147
	global_load_lds_dwordx4 v144, s[4:5]
	s_mov_b32 m0, s35
	s_add_u32 s4, s38, 0x40000
	global_load_lds_dwordx4 v146, s[38:39]
	s_mov_b32 m0, s47
	s_addc_u32 s5, s39, 0
	s_add_i32 s48, s35, 0x4000
	global_load_lds_dwordx4 v144, s[38:39]
	s_mov_b32 m0, s48
	s_add_i32 s49, s35, 0x6000
	global_load_lds_dwordx4 v146, s[4:5]
	s_mov_b32 m0, s49
	s_cmp_eq_u32 s7, 1
	global_load_lds_dwordx4 v144, s[4:5]
	s_mov_b32 s50, 0
	v_lshl_add_u64 v[6:7], s[42:43], 0, v[146:147]
	v_lshl_add_u64 v[4:5], s[42:43], 0, v[144:145]
	v_lshl_add_u64 v[0:1], s[38:39], 0, v[146:147]
	s_cselect_b64 s[4:5], -1, 0
	s_cmp_lg_u32 s7, 1
	v_lshl_add_u64 v[2:3], s[38:39], 0, v[144:145]
	s_cbranch_scc1 .LBB0_1037
	s_barrier
